# speedup vs baseline: 1.0087x; 1.0087x over previous
; DI int tid_() { int t = threadIdx.x; asm volatile("" : "+v"(t)); return t; }
; DI int bid_() { int b = blockIdx.x; asm volatile("" : "+s"(b)); return b; }
; DI void phase_final_norm(float* x, const float* g, int rows) {
;   const int wid = tid_() >> 6, lane = tid_() & 63;
;   for (int row = bid_() * 8 + wid; row < rows; row += gridDim.x * 8) {
;     float* xr = x + (size_t)row * 1024;
;     float4 v[4]; float ss = 0.f;
; #pragma unroll
;     for (int i = 0; i < 4; ++i) { float4 t = *reinterpret_cast<const float4*>(xr + i * 256 + lane * 4); v[i] = t; ss += t.x * t.x + t.y * t.y + t.z * t.z + t.w * t.w; }
;     ss = wave_sum_l(ss, lane);
;     const float r = rsqrtf(ss * (1.f / 1024.f) + EPS);
; #pragma unroll
;     for (int i = 0; i < 4; ++i) { const float4 gg = *reinterpret_cast<const float4*>(g + i * 256 + lane * 4);
;       float4 o = make_float4(v[i].x * r * gg.x, v[i].y * r * gg.y, v[i].z * r * gg.z, v[i].w * r * gg.w);
;       *reinterpret_cast<float4*>(xr + i * 256 + lane * 4) = o; }
;   }
; }
.LBB0_29:
	s_cmpk_eq_i32 s28, 0x4f
	s_mov_b64 s[14:15], -1
	s_cbranch_scc0 .LBB0_34
	s_waitcnt vmcnt(0)
	v_mov_b32_e32 v0, v232
	v_mov_b32_e32 v1, v232
	s_mov_b32 s2, s98
	v_ashrrev_i32_e32 v0, 6, v0
	s_nop 0
	v_lshl_add_u32 v0, s2, 3, v0
	s_mov_b32 s2, 0xc000
	v_cmp_gt_i32_e32 vcc, s2, v0
	s_and_saveexec_b64 s[14:15], vcc
	s_cbranch_execz .LBB0_33
	v_lshlrev_b32_e32 v1, 2, v1
	v_and_b32_e32 v2, 0xfc, v1
	v_bfrev_b32_e32 v3, 0.5
	s_movk_i32 s2, 0x80
	v_lshlrev_b32_e32 v96, 2, v2
	v_bitop3_b32 v6, v1, 64, v3 bitop3:0x6c
	v_bitop3_b32 v7, v1, s2, v3 bitop3:0x6c
	v_lshl_add_u64 v[2:3], s[22:23], 0, v[96:97]
	global_load_dwordx4 v[48:51], v[2:3], off
	global_load_dwordx4 v[52:55], v[2:3], off offset:1024
	global_load_dwordx4 v[56:59], v[2:3], off offset:2048
	global_load_dwordx4 v[60:63], v[2:3], off offset:3072
	v_lshl_add_u64 v[4:5], s[24:25], 0, v[96:97]
	s_mov_b64 s[36:37], 0
.LBB0_32:
	v_ashrrev_i32_e32 v1, 31, v0
	v_lshlrev_b64 v[8:9], 12, v[0:1]
	v_lshl_add_u64 v[28:29], v[4:5], 0, v[8:9]
	global_load_dwordx4 v[8:11], v[28:29], off
	global_load_dwordx4 v[12:15], v[28:29], off offset:1024
	global_load_dwordx4 v[16:19], v[28:29], off offset:2048
	global_load_dwordx4 v[20:23], v[28:29], off offset:3072
	v_add_u32_e32 v0, s99, v0
	s_mov_b32 s2, 0xbfff
	s_waitcnt vmcnt(3)
	v_mov_b32_e32 v32, v9
	s_waitcnt vmcnt(2)
	v_mov_b32_e32 v33, v13
	v_mov_b32_e32 v30, v8
	v_mov_b32_e32 v31, v12
	s_waitcnt vmcnt(1)
	v_mov_b32_e32 v40, v17
	s_waitcnt vmcnt(0)
	v_mov_b32_e32 v41, v21
	v_pk_mul_f32 v[32:33], v[32:33], v[32:33]
	v_mov_b32_e32 v34, v10
	v_mov_b32_e32 v35, v14
	v_mov_b32_e32 v38, v16
	v_mov_b32_e32 v39, v20
	v_pk_mul_f32 v[40:41], v[40:41], v[40:41]
	v_pk_fma_f32 v[30:31], v[30:31], v[30:31], v[32:33]
	v_mov_b32_e32 v36, v11
	v_mov_b32_e32 v37, v15
	v_mov_b32_e32 v42, v18
	v_mov_b32_e32 v43, v22
	v_pk_fma_f32 v[32:33], v[38:39], v[38:39], v[40:41]
	v_pk_fma_f32 v[30:31], v[34:35], v[34:35], v[30:31]
	v_mov_b32_e32 v44, v19
	v_mov_b32_e32 v45, v23
	v_pk_fma_f32 v[32:33], v[42:43], v[42:43], v[32:33]
	v_pk_fma_f32 v[30:31], v[36:37], v[36:37], v[30:31]
	v_pk_fma_f32 v[32:33], v[44:45], v[44:45], v[32:33]
	v_add_f32_e32 v1, v30, v31
	v_add_f32_e32 v1, v1, v32
	v_add_f32_e32 v1, v1, v33
	s_nop 1
	v_add_f32_dpp v1, v1, v1 quad_perm:[1,0,3,2] row_mask:0xf bank_mask:0xf bound_ctrl:1
	s_nop 1
	v_add_f32_dpp v1, v1, v1 quad_perm:[2,3,0,1] row_mask:0xf bank_mask:0xf bound_ctrl:1
	s_nop 1
	v_add_f32_dpp v1, v1, v1 row_half_mirror row_mask:0xf bank_mask:0xf bound_ctrl:1
	s_nop 1
	v_add_f32_dpp v1, v1, v1 row_mirror row_mask:0xf bank_mask:0xf bound_ctrl:1
	ds_bpermute_b32 v30, v6, v1
	s_waitcnt lgkmcnt(0)
	v_add_f32_e32 v1, v1, v30
	ds_bpermute_b32 v30, v7, v1
	s_waitcnt lgkmcnt(0)
	v_add_f32_e32 v1, v1, v30
	v_fmamk_f32 v1, v1, 0x3a800000, v233
	v_mul_f32_e32 v30, 0x4b800000, v1
	v_cmp_gt_f32_e32 vcc, s94, v1
	s_nop 1
	v_cndmask_b32_e32 v1, v1, v30, vcc
	v_rsq_f32_e32 v1, v1
	s_nop 0
	v_mul_f32_e32 v30, 0x45800000, v1
	v_cndmask_b32_e32 v30, v1, v30, vcc
	v_pk_mul_f32 v[8:9], v[8:9], v[30:31] op_sel_hi:[1,0]
	v_pk_mul_f32 v[10:11], v[10:11], v[30:31] op_sel_hi:[1,0]
	v_pk_mul_f32 v[8:9], v[48:49], v[8:9]
	v_pk_mul_f32 v[10:11], v[50:51], v[10:11]
	global_store_dwordx4 v[28:29], v[8:11], off
	v_pk_mul_f32 v[12:13], v[12:13], v[30:31] op_sel_hi:[1,0]
	v_pk_mul_f32 v[14:15], v[14:15], v[30:31] op_sel_hi:[1,0]
	v_cmp_lt_i32_e32 vcc, s2, v0
	s_or_b64 s[36:37], vcc, s[36:37]
	v_pk_mul_f32 v[12:13], v[52:53], v[12:13]
	v_pk_mul_f32 v[14:15], v[54:55], v[14:15]
	global_store_dwordx4 v[28:29], v[12:15], off offset:1024
	v_pk_mul_f32 v[16:17], v[16:17], v[30:31] op_sel_hi:[1,0]
	v_pk_mul_f32 v[18:19], v[18:19], v[30:31] op_sel_hi:[1,0]
	v_pk_mul_f32 v[16:17], v[16:17], v[56:57]
	v_pk_mul_f32 v[18:19], v[18:19], v[58:59]
	global_store_dwordx4 v[28:29], v[16:19], off offset:2048
	v_pk_mul_f32 v[20:21], v[20:21], v[30:31] op_sel_hi:[1,0]
	v_pk_mul_f32 v[22:23], v[22:23], v[30:31] op_sel_hi:[1,0]
	v_pk_mul_f32 v[20:21], v[20:21], v[60:61]
	v_pk_mul_f32 v[22:23], v[22:23], v[62:63]
	global_store_dwordx4 v[28:29], v[20:23], off offset:3072
	s_andn2_b64 exec, exec, s[36:37]
	s_cbranch_execnz .LBB0_32
